# instruction selection: accumulator clears before each GEMM unit as 64 v_mov_b64 instead of 128 v_mov_b32
# speedup vs baseline: 1.0042x; 1.0042x over previous
; template <class Epi, bool ALIGN_EPI, bool SP2 = PG8_SP2_DEFAULT>
; __device__ __forceinline__ void gemm_phase(LAS unsigned char* lds, const Gemm g, const StaticOrder& S, const Epi& E) {
;     ...
;         const bool has_next = S.next(ui + 1, nxt);
;         const char* nA = has_next ? PG8_ABASE(nxt) : cA; const char* nB = has_next ? (const char*)g.Bt + (size_t)nxt.pn * tstepB : cB;
;     ...
;         for (int a = 0; a < 2; ++a)
; #pragma unroll
;             for (int b = 0; b < 2; ++b)
; #pragma unroll
;                 for (int m = 0; m < 4; ++m)
; #pragma unroll
;                     for (int n = 0; n < 2; ++n) acc[a][b][m][n] = (f32x4){0.f, 0.f, 0.f, 0.f};
;         cur = nxt; cA = nA; cB = nB; ++ui;
.LBB0_249:
	s_ashr_i32 s13, s12, 31
	s_lshl_b64 s[14:15], s[12:13], 21
	s_add_u32 s14, s86, s14
	s_addc_u32 s15, s87, s15
	s_and_b64 s[16:17], s[0:1], exec
	s_cselect_b32 s13, s15, s19
	s_cselect_b32 s40, s14, s18
	s_ashr_i32 s11, s10, 31
	s_lshl_b64 s[16:17], s[10:11], 21
	s_add_u32 s16, s60, s16
	s_addc_u32 s17, s61, s17
	s_and_b64 s[22:23], s[0:1], exec
	s_cselect_b32 s11, s17, s21
	s_cselect_b32 s41, s16, s20
	s_add_u32 s18, s18, 0x100080
	s_addc_u32 s19, s19, 0
	s_add_u32 s42, s20, 0x100
	s_addc_u32 s43, s21, 0
	s_mov_b32 s44, -2
	v_mov_b64_e32 v[0:1], 0
	v_mov_b64_e32 v[2:3], 0
	v_mov_b64_e32 v[4:5], 0
	v_mov_b64_e32 v[6:7], 0
	v_mov_b64_e32 v[8:9], 0
	v_mov_b64_e32 v[10:11], 0
	v_mov_b64_e32 v[12:13], 0
	v_mov_b64_e32 v[14:15], 0
	v_mov_b64_e32 v[16:17], 0
	v_mov_b64_e32 v[18:19], 0
	v_mov_b64_e32 v[20:21], 0
	v_mov_b64_e32 v[22:23], 0
	v_mov_b64_e32 v[24:25], 0
	v_mov_b64_e32 v[26:27], 0
	v_mov_b64_e32 v[28:29], 0
	v_mov_b64_e32 v[30:31], 0
	v_mov_b64_e32 v[32:33], 0
	v_mov_b64_e32 v[34:35], 0
	v_mov_b64_e32 v[36:37], 0
	v_mov_b64_e32 v[38:39], 0
	v_mov_b64_e32 v[40:41], 0
	v_mov_b64_e32 v[42:43], 0
	v_mov_b64_e32 v[44:45], 0
	v_mov_b64_e32 v[46:47], 0
	v_mov_b64_e32 v[48:49], 0
	v_mov_b64_e32 v[50:51], 0
	v_mov_b64_e32 v[52:53], 0
	v_mov_b64_e32 v[54:55], 0
	v_mov_b64_e32 v[56:57], 0
	v_mov_b64_e32 v[58:59], 0
	v_mov_b64_e32 v[60:61], 0
	v_mov_b64_e32 v[62:63], 0
	v_mov_b64_e32 v[64:65], 0
	v_mov_b64_e32 v[66:67], 0
	v_mov_b64_e32 v[68:69], 0
	v_mov_b64_e32 v[70:71], 0
	v_mov_b64_e32 v[72:73], 0
	v_mov_b64_e32 v[74:75], 0
	v_mov_b64_e32 v[76:77], 0
	v_mov_b64_e32 v[78:79], 0
	v_mov_b64_e32 v[80:81], 0
	v_mov_b64_e32 v[82:83], 0
	v_mov_b64_e32 v[84:85], 0
	v_mov_b64_e32 v[86:87], 0
	v_mov_b64_e32 v[88:89], 0
	v_mov_b64_e32 v[90:91], 0
	v_mov_b64_e32 v[92:93], 0
	v_mov_b64_e32 v[94:95], 0
	v_mov_b64_e32 v[96:97], 0
	v_mov_b64_e32 v[98:99], 0
	v_mov_b64_e32 v[100:101], 0
	v_mov_b64_e32 v[102:103], 0
	v_mov_b64_e32 v[104:105], 0
	v_mov_b64_e32 v[106:107], 0
	v_mov_b64_e32 v[108:109], 0
	v_mov_b64_e32 v[110:111], 0
	v_mov_b64_e32 v[112:113], 0
	v_mov_b64_e32 v[114:115], 0
	v_mov_b64_e32 v[116:117], 0
	v_mov_b64_e32 v[118:119], 0
	v_mov_b64_e32 v[120:121], 0
	v_mov_b64_e32 v[122:123], 0
	v_mov_b64_e32 v[124:125], 0
	v_mov_b64_e32 v[126:127], 0

; template <class Epi, bool ALIGN_EPI, bool SP2 = PG8_SP2_DEFAULT>
; __device__ __forceinline__ void gemm_phase(LAS unsigned char* lds, const Gemm g, const StaticOrder& S, const Epi& E) {
;     ...
;         const bool has_next = S.next(ui + 1, nxt);
;         const char* nA = has_next ? PG8_ABASE(nxt) : cA; const char* nB = has_next ? (const char*)g.Bt + (size_t)nxt.pn * tstepB : cB;
;     ...
;         for (int a = 0; a < 2; ++a)
; #pragma unroll
;             for (int b = 0; b < 2; ++b)
; #pragma unroll
;                 for (int m = 0; m < 4; ++m)
; #pragma unroll
;                     for (int n = 0; n < 2; ++n) acc[a][b][m][n] = (f32x4){0.f, 0.f, 0.f, 0.f};
;         cur = nxt; cA = nA; cB = nB; ++ui;
.LBB0_427:
	s_ashr_i32 s16, s12, 1
	s_ashr_i32 s17, s16, 31
	s_lshl_b64 s[16:17], s[16:17], 23
	s_add_u32 s13, s33, s16
	s_addc_u32 s18, s44, s17
	s_ashr_i32 s15, s14, 31
	s_lshl_b64 s[16:17], s[14:15], 18
	s_add_u32 s16, s13, s16
	s_addc_u32 s17, s18, s17
	s_and_b64 s[18:19], s[0:1], exec
	s_cselect_b32 s15, s17, s23
	s_cselect_b32 s47, s16, s22
	s_ashr_i32 s13, s12, 31
	s_lshl_b64 s[18:19], s[12:13], 18
	s_add_u32 s18, s70, s18
	s_addc_u32 s19, s71, s19
	s_and_b64 s[26:27], s[0:1], exec
	s_cselect_b32 s13, s19, s25
	s_cselect_b32 s48, s18, s24
	s_add_u32 s22, s22, 0x20080
	s_addc_u32 s23, s23, 0
	s_add_u32 s49, s24, 0x100
	s_addc_u32 s50, s25, 0
	s_mov_b32 s51, -2
	s_waitcnt vmcnt(0)
	v_mov_b64_e32 v[0:1], 0
	v_mov_b64_e32 v[2:3], 0
	v_mov_b64_e32 v[4:5], 0
	v_mov_b64_e32 v[6:7], 0
	v_mov_b64_e32 v[8:9], 0
	v_mov_b64_e32 v[10:11], 0
	v_mov_b64_e32 v[12:13], 0
	v_mov_b64_e32 v[14:15], 0
	v_mov_b64_e32 v[16:17], 0
	v_mov_b64_e32 v[18:19], 0
	v_mov_b64_e32 v[20:21], 0
	v_mov_b64_e32 v[22:23], 0
	v_mov_b64_e32 v[24:25], 0
	v_mov_b64_e32 v[26:27], 0
	v_mov_b64_e32 v[28:29], 0
	v_mov_b64_e32 v[30:31], 0
	v_mov_b64_e32 v[32:33], 0
	v_mov_b64_e32 v[34:35], 0
	v_mov_b64_e32 v[36:37], 0
	v_mov_b64_e32 v[38:39], 0
	v_mov_b64_e32 v[40:41], 0
	v_mov_b64_e32 v[42:43], 0
	v_mov_b64_e32 v[44:45], 0
	v_mov_b64_e32 v[46:47], 0
	v_mov_b64_e32 v[48:49], 0
	v_mov_b64_e32 v[50:51], 0
	v_mov_b64_e32 v[52:53], 0
	v_mov_b64_e32 v[54:55], 0
	v_mov_b64_e32 v[56:57], 0
	v_mov_b64_e32 v[58:59], 0
	v_mov_b64_e32 v[60:61], 0
	v_mov_b64_e32 v[62:63], 0
	v_mov_b64_e32 v[64:65], 0
	v_mov_b64_e32 v[66:67], 0
	v_mov_b64_e32 v[68:69], 0
	v_mov_b64_e32 v[70:71], 0
	v_mov_b64_e32 v[72:73], 0
	v_mov_b64_e32 v[74:75], 0
	v_mov_b64_e32 v[76:77], 0
	v_mov_b64_e32 v[78:79], 0
	v_mov_b64_e32 v[80:81], 0
	v_mov_b64_e32 v[82:83], 0
	v_mov_b64_e32 v[84:85], 0
	v_mov_b64_e32 v[86:87], 0
	v_mov_b64_e32 v[88:89], 0
	v_mov_b64_e32 v[90:91], 0
	v_mov_b64_e32 v[92:93], 0
	v_mov_b64_e32 v[94:95], 0
	v_mov_b64_e32 v[96:97], 0
	v_mov_b64_e32 v[98:99], 0
	v_mov_b64_e32 v[100:101], 0
	v_mov_b64_e32 v[102:103], 0
	v_mov_b64_e32 v[104:105], 0
	v_mov_b64_e32 v[106:107], 0
	v_mov_b64_e32 v[108:109], 0
	v_mov_b64_e32 v[110:111], 0
	v_mov_b64_e32 v[112:113], 0
	v_mov_b64_e32 v[114:115], 0
	v_mov_b64_e32 v[116:117], 0
	v_mov_b64_e32 v[118:119], 0
	v_mov_b64_e32 v[120:121], 0
	v_mov_b64_e32 v[122:123], 0
	v_mov_b64_e32 v[124:125], 0
	v_mov_b64_e32 v[126:127], 0

; template <class Epi, bool ALIGN_EPI, bool SP2 = PG8_SP2_DEFAULT>
; __device__ __forceinline__ void gemm_phase(LAS unsigned char* lds, const Gemm g, const StaticOrder& S, const Epi& E) {
;     ...
;         const bool has_next = S.next(ui + 1, nxt);
;         const char* nA = has_next ? PG8_ABASE(nxt) : cA; const char* nB = has_next ? (const char*)g.Bt + (size_t)nxt.pn * tstepB : cB;
;     ...
;         for (int a = 0; a < 2; ++a)
; #pragma unroll
;             for (int b = 0; b < 2; ++b)
; #pragma unroll
;                 for (int m = 0; m < 4; ++m)
; #pragma unroll
;                     for (int n = 0; n < 2; ++n) acc[a][b][m][n] = (f32x4){0.f, 0.f, 0.f, 0.f};
;         cur = nxt; cA = nA; cB = nB; ++ui;
.LBB0_505:
	s_ashr_i32 s19, s18, 31
	s_lshl_b64 s[20:21], s[18:19], 21
	s_add_u32 s20, s96, s20
	s_addc_u32 s21, s97, s21
	s_and_b64 s[22:23], s[6:7], exec
	s_cselect_b32 s19, s21, s27
	s_cselect_b32 s25, s20, s26
	s_ashr_i32 s3, s2, 31
	s_lshl_b64 s[22:23], s[2:3], 21
	s_add_u32 s22, s88, s22
	s_addc_u32 s23, s89, s23
	s_and_b64 s[30:31], s[6:7], exec
	s_cselect_b32 s3, s23, s29
	s_cselect_b32 s47, s22, s28
	s_add_u32 s26, s26, 0x100080
	s_addc_u32 s27, s27, 0
	s_add_u32 s48, s28, 0x100
	s_addc_u32 s49, s29, 0
	s_mov_b32 s50, -2
	s_waitcnt lgkmcnt(0)
	v_mov_b64_e32 v[0:1], 0
	v_mov_b64_e32 v[2:3], 0
	v_mov_b64_e32 v[4:5], 0
	v_mov_b64_e32 v[6:7], 0
	v_mov_b64_e32 v[8:9], 0
	v_mov_b64_e32 v[10:11], 0
	v_mov_b64_e32 v[12:13], 0
	v_mov_b64_e32 v[14:15], 0
	v_mov_b64_e32 v[16:17], 0
	v_mov_b64_e32 v[18:19], 0
	v_mov_b64_e32 v[20:21], 0
	v_mov_b64_e32 v[22:23], 0
	v_mov_b64_e32 v[24:25], 0
	v_mov_b64_e32 v[26:27], 0
	v_mov_b64_e32 v[28:29], 0
	v_mov_b64_e32 v[30:31], 0
	v_mov_b64_e32 v[32:33], 0
	v_mov_b64_e32 v[34:35], 0
	v_mov_b64_e32 v[36:37], 0
	v_mov_b64_e32 v[38:39], 0
	v_mov_b64_e32 v[40:41], 0
	v_mov_b64_e32 v[42:43], 0
	v_mov_b64_e32 v[44:45], 0
	v_mov_b64_e32 v[46:47], 0
	v_mov_b64_e32 v[48:49], 0
	v_mov_b64_e32 v[50:51], 0
	v_mov_b64_e32 v[52:53], 0
	v_mov_b64_e32 v[54:55], 0
	v_mov_b64_e32 v[56:57], 0
	v_mov_b64_e32 v[58:59], 0
	v_mov_b64_e32 v[60:61], 0
	v_mov_b64_e32 v[62:63], 0
	v_mov_b64_e32 v[64:65], 0
	v_mov_b64_e32 v[66:67], 0
	v_mov_b64_e32 v[68:69], 0
	v_mov_b64_e32 v[70:71], 0
	v_mov_b64_e32 v[72:73], 0
	v_mov_b64_e32 v[74:75], 0
	v_mov_b64_e32 v[76:77], 0
	v_mov_b64_e32 v[78:79], 0
	v_mov_b64_e32 v[80:81], 0
	v_mov_b64_e32 v[82:83], 0
	v_mov_b64_e32 v[84:85], 0
	v_mov_b64_e32 v[86:87], 0
	v_mov_b64_e32 v[88:89], 0
	v_mov_b64_e32 v[90:91], 0
	v_mov_b64_e32 v[92:93], 0
	v_mov_b64_e32 v[94:95], 0
	v_mov_b64_e32 v[96:97], 0
	v_mov_b64_e32 v[98:99], 0
	v_mov_b64_e32 v[100:101], 0
	v_mov_b64_e32 v[102:103], 0
	v_mov_b64_e32 v[104:105], 0
	v_mov_b64_e32 v[106:107], 0
	v_mov_b64_e32 v[108:109], 0
	v_mov_b64_e32 v[110:111], 0
	v_mov_b64_e32 v[112:113], 0
	v_mov_b64_e32 v[114:115], 0
	v_mov_b64_e32 v[116:117], 0
	v_mov_b64_e32 v[118:119], 0
	v_mov_b64_e32 v[120:121], 0
	v_mov_b64_e32 v[122:123], 0
	v_mov_b64_e32 v[124:125], 0
	v_mov_b64_e32 v[126:127], 0

; template <class Epi, bool ALIGN_EPI, bool SP2 = PG8_SP2_DEFAULT>
; __device__ __forceinline__ void gemm_phase(LAS unsigned char* lds, const Gemm g, const StaticOrder& S, const Epi& E) {
;     ...
;         const bool has_next = S.next(ui + 1, nxt);
;         const char* nA = has_next ? PG8_ABASE(nxt) : cA; const char* nB = has_next ? (const char*)g.Bt + (size_t)nxt.pn * tstepB : cB;
;     ...
;         for (int a = 0; a < 2; ++a)
; #pragma unroll
;             for (int b = 0; b < 2; ++b)
; #pragma unroll
;                 for (int m = 0; m < 4; ++m)
; #pragma unroll
;                     for (int n = 0; n < 2; ++n) acc[a][b][m][n] = (f32x4){0.f, 0.f, 0.f, 0.f};
;         cur = nxt; cA = nA; cB = nB; ++ui;
.LBB0_597:
	s_ashr_i32 s17, s16, 31
	s_lshl_b64 s[18:19], s[16:17], 21
	s_add_u32 s18, s92, s18
	s_addc_u32 s19, s93, s19
	s_and_b64 s[20:21], s[4:5], exec
	s_cselect_b32 s3, s19, s23
	s_cselect_b32 s7, s18, s22
	s_ashr_i32 s9, s8, 31
	s_lshl_b64 s[20:21], s[8:9], 21
	s_add_u32 s20, s90, s20
	s_addc_u32 s21, s91, s21
	s_and_b64 s[26:27], s[4:5], exec
	s_cselect_b32 s9, s21, s25
	s_cselect_b32 s17, s20, s24
	s_add_u32 s22, s22, 0x100080
	s_addc_u32 s23, s23, 0
	s_add_u32 s44, s24, 0x100
	s_addc_u32 s45, s25, 0
	s_mov_b32 s47, -2
	v_mov_b64_e32 v[0:1], 0
	v_mov_b64_e32 v[2:3], 0
	v_mov_b64_e32 v[4:5], 0
	v_mov_b64_e32 v[6:7], 0
	v_mov_b64_e32 v[8:9], 0
	v_mov_b64_e32 v[10:11], 0
	v_mov_b64_e32 v[12:13], 0
	v_mov_b64_e32 v[14:15], 0
	v_mov_b64_e32 v[16:17], 0
	v_mov_b64_e32 v[18:19], 0
	v_mov_b64_e32 v[20:21], 0
	v_mov_b64_e32 v[22:23], 0
	v_mov_b64_e32 v[24:25], 0
	v_mov_b64_e32 v[26:27], 0
	v_mov_b64_e32 v[28:29], 0
	v_mov_b64_e32 v[30:31], 0
	v_mov_b64_e32 v[32:33], 0
	v_mov_b64_e32 v[34:35], 0
	v_mov_b64_e32 v[36:37], 0
	v_mov_b64_e32 v[38:39], 0
	v_mov_b64_e32 v[40:41], 0
	v_mov_b64_e32 v[42:43], 0
	v_mov_b64_e32 v[44:45], 0
	v_mov_b64_e32 v[46:47], 0
	v_mov_b64_e32 v[48:49], 0
	v_mov_b64_e32 v[50:51], 0
	v_mov_b64_e32 v[52:53], 0
	v_mov_b64_e32 v[54:55], 0
	v_mov_b64_e32 v[56:57], 0
	v_mov_b64_e32 v[58:59], 0
	v_mov_b64_e32 v[60:61], 0
	v_mov_b64_e32 v[62:63], 0
	v_mov_b64_e32 v[64:65], 0
	v_mov_b64_e32 v[66:67], 0
	v_mov_b64_e32 v[68:69], 0
	v_mov_b64_e32 v[70:71], 0
	v_mov_b64_e32 v[72:73], 0
	v_mov_b64_e32 v[74:75], 0
	v_mov_b64_e32 v[76:77], 0
	v_mov_b64_e32 v[78:79], 0
	v_mov_b64_e32 v[80:81], 0
	v_mov_b64_e32 v[82:83], 0
	v_mov_b64_e32 v[84:85], 0
	v_mov_b64_e32 v[86:87], 0
	v_mov_b64_e32 v[88:89], 0
	v_mov_b64_e32 v[90:91], 0
	v_mov_b64_e32 v[92:93], 0
	v_mov_b64_e32 v[94:95], 0
	v_mov_b64_e32 v[96:97], 0
	v_mov_b64_e32 v[98:99], 0
	v_mov_b64_e32 v[100:101], 0
	v_mov_b64_e32 v[102:103], 0
	v_mov_b64_e32 v[104:105], 0
	v_mov_b64_e32 v[106:107], 0
	v_mov_b64_e32 v[108:109], 0
	v_mov_b64_e32 v[110:111], 0
	v_mov_b64_e32 v[112:113], 0
	v_mov_b64_e32 v[114:115], 0
	v_mov_b64_e32 v[116:117], 0
	v_mov_b64_e32 v[118:119], 0
	v_mov_b64_e32 v[120:121], 0
	v_mov_b64_e32 v[122:123], 0
	v_mov_b64_e32 v[124:125], 0
	v_mov_b64_e32 v[126:127], 0

; template <class Epi, bool ALIGN_EPI, bool SP2 = PG8_SP2_DEFAULT>
; __device__ __forceinline__ void gemm_phase(LAS unsigned char* lds, const Gemm g, const StaticOrder& S, const Epi& E) {
;     ...
;         for (int a = 0; a < 2; ++a)
; #pragma unroll
;             for (int b = 0; b < 2; ++b)
; #pragma unroll
;                 for (int m = 0; m < 4; ++m)
; #pragma unroll
;                     for (int n = 0; n < 2; ++n) acc[a][b][m][n] = (f32x4){0.f, 0.f, 0.f, 0.f};
;         cur = nxt; cA = nA; cB = nB; ++ui;
.LBB0_803:
	s_add_u32 s47, s22, 0x100
	s_addc_u32 s48, s23, 0
	s_mov_b32 s49, -2
	v_mov_b64_e32 v[0:1], 0
	v_mov_b64_e32 v[2:3], 0
	v_mov_b64_e32 v[4:5], 0
	v_mov_b64_e32 v[6:7], 0
	v_mov_b64_e32 v[8:9], 0
	v_mov_b64_e32 v[10:11], 0
	v_mov_b64_e32 v[12:13], 0
	v_mov_b64_e32 v[14:15], 0
	v_mov_b64_e32 v[16:17], 0
	v_mov_b64_e32 v[18:19], 0
	v_mov_b64_e32 v[20:21], 0
	v_mov_b64_e32 v[22:23], 0
	v_mov_b64_e32 v[24:25], 0
	v_mov_b64_e32 v[26:27], 0
	v_mov_b64_e32 v[28:29], 0
	v_mov_b64_e32 v[30:31], 0
	v_mov_b64_e32 v[32:33], 0
	v_mov_b64_e32 v[34:35], 0
	v_mov_b64_e32 v[36:37], 0
	v_mov_b64_e32 v[38:39], 0
	v_mov_b64_e32 v[40:41], 0
	v_mov_b64_e32 v[42:43], 0
	v_mov_b64_e32 v[44:45], 0
	v_mov_b64_e32 v[46:47], 0
	v_mov_b64_e32 v[48:49], 0
	v_mov_b64_e32 v[50:51], 0
	v_mov_b64_e32 v[52:53], 0
	v_mov_b64_e32 v[54:55], 0
	v_mov_b64_e32 v[56:57], 0
	v_mov_b64_e32 v[58:59], 0
	v_mov_b64_e32 v[60:61], 0
	v_mov_b64_e32 v[62:63], 0
	v_mov_b64_e32 v[64:65], 0
	v_mov_b64_e32 v[66:67], 0
	v_mov_b64_e32 v[68:69], 0
	v_mov_b64_e32 v[70:71], 0
	v_mov_b64_e32 v[72:73], 0
	v_mov_b64_e32 v[74:75], 0
	v_mov_b64_e32 v[76:77], 0
	v_mov_b64_e32 v[78:79], 0
	v_mov_b64_e32 v[80:81], 0
	v_mov_b64_e32 v[82:83], 0
	v_mov_b64_e32 v[84:85], 0
	v_mov_b64_e32 v[86:87], 0
	v_mov_b64_e32 v[88:89], 0
	v_mov_b64_e32 v[90:91], 0
	v_mov_b64_e32 v[92:93], 0
	v_mov_b64_e32 v[94:95], 0
	v_mov_b64_e32 v[96:97], 0
	v_mov_b64_e32 v[98:99], 0
	v_mov_b64_e32 v[100:101], 0
	v_mov_b64_e32 v[102:103], 0
	v_mov_b64_e32 v[104:105], 0
	v_mov_b64_e32 v[106:107], 0
	v_mov_b64_e32 v[108:109], 0
	v_mov_b64_e32 v[110:111], 0
	v_mov_b64_e32 v[112:113], 0
	v_mov_b64_e32 v[114:115], 0
	v_mov_b64_e32 v[116:117], 0
	v_mov_b64_e32 v[118:119], 0
	v_mov_b64_e32 v[120:121], 0
	v_mov_b64_e32 v[122:123], 0
	v_mov_b64_e32 v[124:125], 0
	v_mov_b64_e32 v[126:127], 0
